# accumulator zeroing between GEMM units with v_mov_b64 (half the instructions)
# speedup vs baseline: 1.0172x; 1.0042x over previous
; #define PG8_ZERO_ACC() do { _Pragma("unroll") for (int a = 0; a < 2; ++a) _Pragma("unroll") for (int b = 0; b < 2; ++b) _Pragma("unroll") for (int m = 0; m < 4; ++m) _Pragma("unroll") for (int n = 0; n < 2; ++n) acc[a][b][m][n] = (f32x4){0.f, 0.f, 0.f, 0.f}; } while (0)
; template <class Epi, class Sched, bool ALIGN_EPI = false, bool SP2 = false>
; __device__ __forceinline__ void gemm_phase(PG8_LAS unsigned char* lds, const Gemm g, const Sched& S, const Epi& E, const int wave_s) {
;     ...
;         const bool has_next = S.next(ui + 1, nxt);
;         const char* nA = has_next ? (const char*)g.A + (size_t)nxt.pm * tstep + (size_t)nxt.k0 * kstep : cA; const char* nB = has_next ? (const char*)g.Bt + (size_t)nxt.pn * tstep + (size_t)nxt.k0 * kstep : cB;
;     ...
;         if constexpr (Epi::INIT_ACC) {
;             if (Sched::STREAMK && nxt.kind == 2) S.load_partial(acc, tid, wid, lane);
;             else if (nxt.kind == 0) { int fr_i = fr, fq_i = fq; asm volatile("" : "+v"(fr_i), "+v"(fq_i)); E.init(acc, nxt, wr, wc, fr_i, fq_i); }
;             else PG8_ZERO_ACC();
;         } else {
;             if (Sched::STREAMK && nxt.kind == 2) S.load_partial(acc, tid, wid, lane);
;             else PG8_ZERO_ACC();
.LBB0_300:
	s_ashr_i32 s25, s24, 31
	s_lshl_b64 s[26:27], s[24:25], 19
	s_add_u32 s26, s38, s26
	s_addc_u32 s27, s39, s27
	s_and_b64 s[28:29], s[6:7], exec
	s_cselect_b32 s9, s27, s35
	s_cselect_b32 s25, s26, s34
	s_ashr_i32 s23, s22, 31
	s_lshl_b64 s[28:29], s[22:23], 19
	s_add_u32 s28, s40, s28
	s_addc_u32 s29, s41, s29
	s_and_b64 s[36:37], s[6:7], exec
	s_cselect_b32 s23, s29, s3
	s_cselect_b32 s31, s28, s2
	s_add_u32 s34, s34, 0x40080
	s_addc_u32 s35, s35, 0
	s_add_u32 s52, s2, 0x100
	v_mov_b32_e32 v0, 0
	s_addc_u32 s53, s3, 0
	s_mov_b32 s54, -2
	v_mov_b32_e32 v1, v0
	v_mov_b64_e32 v[2:3], v[0:1]
	v_mov_b64_e32 v[4:5], v[0:1]
	v_mov_b64_e32 v[6:7], v[0:1]
	v_mov_b64_e32 v[16:17], v[0:1]
	v_mov_b64_e32 v[18:19], v[0:1]
	v_mov_b64_e32 v[20:21], v[0:1]
	v_mov_b64_e32 v[22:23], v[0:1]
	v_mov_b64_e32 v[32:33], v[0:1]
	v_mov_b64_e32 v[34:35], v[0:1]
	v_mov_b64_e32 v[36:37], v[0:1]
	v_mov_b64_e32 v[38:39], v[0:1]
	v_mov_b64_e32 v[48:49], v[0:1]
	v_mov_b64_e32 v[50:51], v[0:1]
	v_mov_b64_e32 v[52:53], v[0:1]
	v_mov_b64_e32 v[54:55], v[0:1]
	v_mov_b64_e32 v[8:9], v[0:1]
	v_mov_b64_e32 v[10:11], v[0:1]
	v_mov_b64_e32 v[12:13], v[0:1]
	v_mov_b64_e32 v[14:15], v[0:1]
	v_mov_b64_e32 v[24:25], v[0:1]
	v_mov_b64_e32 v[26:27], v[0:1]
	v_mov_b64_e32 v[28:29], v[0:1]
	v_mov_b64_e32 v[30:31], v[0:1]
	v_mov_b64_e32 v[40:41], v[0:1]
	v_mov_b64_e32 v[42:43], v[0:1]
	v_mov_b64_e32 v[44:45], v[0:1]
	v_mov_b64_e32 v[46:47], v[0:1]
	v_mov_b64_e32 v[56:57], v[0:1]
	v_mov_b64_e32 v[58:59], v[0:1]
	v_mov_b64_e32 v[60:61], v[0:1]
	v_mov_b64_e32 v[62:63], v[0:1]
	v_mov_b64_e32 v[64:65], v[0:1]
	v_mov_b64_e32 v[66:67], v[0:1]
	v_mov_b64_e32 v[68:69], v[0:1]
	v_mov_b64_e32 v[70:71], v[0:1]
	v_mov_b64_e32 v[80:81], v[0:1]
	v_mov_b64_e32 v[82:83], v[0:1]
	v_mov_b64_e32 v[84:85], v[0:1]
	v_mov_b64_e32 v[86:87], v[0:1]
	v_mov_b64_e32 v[96:97], v[0:1]
	v_mov_b64_e32 v[98:99], v[0:1]
	v_mov_b64_e32 v[100:101], v[0:1]
	v_mov_b64_e32 v[102:103], v[0:1]
	v_mov_b64_e32 v[112:113], v[0:1]
	v_mov_b64_e32 v[114:115], v[0:1]
	v_mov_b64_e32 v[116:117], v[0:1]
	v_mov_b64_e32 v[118:119], v[0:1]
	v_mov_b64_e32 v[72:73], v[0:1]
	v_mov_b64_e32 v[74:75], v[0:1]
	v_mov_b64_e32 v[76:77], v[0:1]
	v_mov_b64_e32 v[78:79], v[0:1]
	v_mov_b64_e32 v[88:89], v[0:1]
	v_mov_b64_e32 v[90:91], v[0:1]
	v_mov_b64_e32 v[92:93], v[0:1]
	v_mov_b64_e32 v[94:95], v[0:1]
	v_mov_b64_e32 v[104:105], v[0:1]
	v_mov_b64_e32 v[106:107], v[0:1]
	v_mov_b64_e32 v[108:109], v[0:1]
	v_mov_b64_e32 v[110:111], v[0:1]
	v_mov_b64_e32 v[120:121], v[0:1]
	v_mov_b64_e32 v[122:123], v[0:1]
	v_mov_b64_e32 v[124:125], v[0:1]
	v_mov_b64_e32 v[126:127], v[0:1]

; #define PG8_ZERO_ACC() do { _Pragma("unroll") for (int a = 0; a < 2; ++a) _Pragma("unroll") for (int b = 0; b < 2; ++b) _Pragma("unroll") for (int m = 0; m < 4; ++m) _Pragma("unroll") for (int n = 0; n < 2; ++n) acc[a][b][m][n] = (f32x4){0.f, 0.f, 0.f, 0.f}; } while (0)
; template <class Epi, class Sched, bool ALIGN_EPI = false, bool SP2 = false>
; __device__ __forceinline__ void gemm_phase(PG8_LAS unsigned char* lds, const Gemm g, const Sched& S, const Epi& E, const int wave_s) {
;     ...
;         const bool has_next = S.next(ui + 1, nxt);
;         const char* nA = has_next ? (const char*)g.A + (size_t)nxt.pm * tstep + (size_t)nxt.k0 * kstep : cA; const char* nB = has_next ? (const char*)g.Bt + (size_t)nxt.pn * tstep + (size_t)nxt.k0 * kstep : cB;
;     ...
;         if constexpr (Epi::INIT_ACC) {
;             if (Sched::STREAMK && nxt.kind == 2) S.load_partial(acc, tid, wid, lane);
;             else if (nxt.kind == 0) { int fr_i = fr, fq_i = fq; asm volatile("" : "+v"(fr_i), "+v"(fq_i)); E.init(acc, nxt, wr, wc, fr_i, fq_i); }
;             else PG8_ZERO_ACC();
;         } else {
;             if (Sched::STREAMK && nxt.kind == 2) S.load_partial(acc, tid, wid, lane);
;             else PG8_ZERO_ACC();
.LBB0_522:
	s_ashr_i32 s19, s18, 31
	s_lshl_b64 s[20:21], s[18:19], 19
	s_add_u32 s20, s28, s20
	s_addc_u32 s21, s29, s21
	s_and_b64 s[22:23], s[6:7], exec
	s_cselect_b32 s19, s21, s25
	s_cselect_b32 s46, s20, s24
	s_ashr_i32 s17, s16, 31
	s_lshl_b64 s[22:23], s[16:17], 19
	s_add_u32 s22, s30, s22
	s_addc_u32 s23, s31, s23
	s_and_b64 s[26:27], s[6:7], exec
	s_cselect_b32 s17, s23, s3
	s_cselect_b32 s47, s22, s2
	s_add_u32 s24, s24, 0x40080
	s_addc_u32 s25, s25, 0
	s_add_u32 s48, s2, 0x100
	v_mov_b32_e32 v0, 0
	s_addc_u32 s49, s3, 0
	s_mov_b32 s50, -2
	v_mov_b32_e32 v1, v0
	v_mov_b64_e32 v[2:3], v[0:1]
	v_mov_b64_e32 v[8:9], v[0:1]
	v_mov_b64_e32 v[10:11], v[0:1]
	v_mov_b64_e32 v[16:17], v[0:1]
	v_mov_b64_e32 v[18:19], v[0:1]
	v_mov_b64_e32 v[24:25], v[0:1]
	v_mov_b64_e32 v[26:27], v[0:1]
	v_mov_b64_e32 v[32:33], v[0:1]
	v_mov_b64_e32 v[34:35], v[0:1]
	v_mov_b64_e32 v[40:41], v[0:1]
	v_mov_b64_e32 v[42:43], v[0:1]
	v_mov_b64_e32 v[48:49], v[0:1]
	v_mov_b64_e32 v[50:51], v[0:1]
	v_mov_b64_e32 v[56:57], v[0:1]
	v_mov_b64_e32 v[58:59], v[0:1]
	v_mov_b64_e32 v[4:5], v[0:1]
	v_mov_b64_e32 v[6:7], v[0:1]
	v_mov_b64_e32 v[12:13], v[0:1]
	v_mov_b64_e32 v[14:15], v[0:1]
	v_mov_b64_e32 v[20:21], v[0:1]
	v_mov_b64_e32 v[22:23], v[0:1]
	v_mov_b64_e32 v[28:29], v[0:1]
	v_mov_b64_e32 v[30:31], v[0:1]
	v_mov_b64_e32 v[36:37], v[0:1]
	v_mov_b64_e32 v[38:39], v[0:1]
	v_mov_b64_e32 v[44:45], v[0:1]
	v_mov_b64_e32 v[46:47], v[0:1]
	v_mov_b64_e32 v[52:53], v[0:1]
	v_mov_b64_e32 v[54:55], v[0:1]
	v_mov_b64_e32 v[60:61], v[0:1]
	v_mov_b64_e32 v[62:63], v[0:1]
	v_mov_b64_e32 v[64:65], v[0:1]
	v_mov_b64_e32 v[66:67], v[0:1]
	v_mov_b64_e32 v[72:73], v[0:1]
	v_mov_b64_e32 v[74:75], v[0:1]
	v_mov_b64_e32 v[80:81], v[0:1]
	v_mov_b64_e32 v[82:83], v[0:1]
	v_mov_b64_e32 v[88:89], v[0:1]
	v_mov_b64_e32 v[90:91], v[0:1]
	v_mov_b64_e32 v[96:97], v[0:1]
	v_mov_b64_e32 v[98:99], v[0:1]
	v_mov_b64_e32 v[104:105], v[0:1]
	v_mov_b64_e32 v[106:107], v[0:1]
	v_mov_b64_e32 v[112:113], v[0:1]
	v_mov_b64_e32 v[114:115], v[0:1]
	v_mov_b64_e32 v[120:121], v[0:1]
	v_mov_b64_e32 v[122:123], v[0:1]
	v_mov_b64_e32 v[68:69], v[0:1]
	v_mov_b64_e32 v[70:71], v[0:1]
	v_mov_b64_e32 v[76:77], v[0:1]
	v_mov_b64_e32 v[78:79], v[0:1]
	v_mov_b64_e32 v[84:85], v[0:1]
	v_mov_b64_e32 v[86:87], v[0:1]
	v_mov_b64_e32 v[92:93], v[0:1]
	v_mov_b64_e32 v[94:95], v[0:1]
	v_mov_b64_e32 v[100:101], v[0:1]
	v_mov_b64_e32 v[102:103], v[0:1]
	v_mov_b64_e32 v[108:109], v[0:1]
	v_mov_b64_e32 v[110:111], v[0:1]
	v_mov_b64_e32 v[116:117], v[0:1]
	v_mov_b64_e32 v[118:119], v[0:1]
	v_mov_b64_e32 v[124:125], v[0:1]
	v_mov_b64_e32 v[126:127], v[0:1]
